# residual-add GEMM epilogues (w_out, w_down): all 16 residual row loads of a tile issued before the LDS staging instead of a serial load-wait-add-store chain
# speedup vs baseline: 1.2483x; 1.0086x over previous
;     ...
; #pragma unroll 1
;     for (int kt = 0; kt < nk - 1; ++kt) {
;       asm volatile("s_waitcnt vmcnt(0) lgkmcnt(0)" ::: "memory");
;       __builtin_amdgcn_s_barrier();
;       asm volatile("" ::: "memory");
;       G3_STEP(kt, true)
;     }
.LBB0_37:
	s_lshl_b32 s11, s9, 1
	s_and_b32 s11, s11, 0x8000
	v_lshl_or_b32 v87, v86, 1, s11
	s_waitcnt vmcnt(0) lgkmcnt(0)
	s_barrier
	v_add3_u32 v100, v87, v84, v83
	v_add3_u32 v87, v87, v82, v83
	ds_read_b128 v[88:91], v100
	ds_read_b128 v[92:95], v100 offset:2048
	ds_read_b128 v[96:99], v100 offset:4096
	ds_read_b128 v[100:103], v100 offset:6144
	ds_read_b128 v[104:107], v87 offset:16384
	ds_read_b128 v[108:111], v87 offset:18432
	ds_read_b128 v[112:115], v87 offset:20480
	ds_read_b128 v[116:119], v87 offset:22528
	v_lshl_or_b32 v87, v85, 1, s11
	v_add3_u32 v132, v87, v84, v83
	v_add3_u32 v87, v87, v82, v83
	ds_read_b128 v[120:123], v132
	ds_read_b128 v[124:127], v132 offset:2048
	ds_read_b128 v[128:131], v132 offset:4096
	ds_read_b128 v[132:135], v132 offset:6144
	ds_read_b128 v[136:139], v87 offset:16384
	ds_read_b128 v[140:143], v87 offset:18432
	ds_read_b128 v[144:147], v87 offset:20480
	ds_read_b128 v[148:151], v87 offset:22528
	s_setprio 1
	s_andn2_b32 s11, 0x8000, s10
	s_waitcnt lgkmcnt(11)
	v_mfma_f32_16x16x32_bf16 v[60:63], v[88:91], v[104:107], v[60:63]
	s_add_i32 s11, s8, s11
	v_lshl_add_u64 v[172:173], v[64:65], 0, s[0:1]
	s_mov_b32 m0, s11
	s_nop 0
	global_load_lds_dwordx4 v[172:173], off
	s_waitcnt lgkmcnt(10)
	v_mfma_f32_16x16x32_bf16 v[56:59], v[88:91], v[108:111], v[56:59]
	v_lshl_add_u64 v[152:153], v[78:79], 0, s[0:1]
	v_lshl_add_u64 v[154:155], v[76:77], 0, s[0:1]
	v_lshl_add_u64 v[156:157], v[74:75], 0, s[0:1]
	v_lshl_add_u64 v[158:159], v[72:73], 0, s[0:1]
	v_lshl_add_u64 v[166:167], v[70:71], 0, s[0:1]
	v_lshl_add_u64 v[168:169], v[68:69], 0, s[0:1]
	v_lshl_add_u64 v[170:171], v[66:67], 0, s[0:1]
	s_waitcnt lgkmcnt(9)
	v_mfma_f32_16x16x32_bf16 v[52:55], v[88:91], v[112:115], v[52:55]
	s_add_i32 s12, s11, 0x400
	s_mov_b32 m0, s12
	s_nop 0
	global_load_lds_dwordx4 v[168:169], off
	s_waitcnt lgkmcnt(8)
	v_mfma_f32_16x16x32_bf16 v[48:51], v[88:91], v[116:119], v[48:51]
	v_mfma_f32_16x16x32_bf16 v[44:47], v[92:95], v[104:107], v[44:47]
	s_add_i32 s12, s11, 0x800
	s_mov_b32 m0, s12
	s_nop 0
	global_load_lds_dwordx4 v[156:157], off
	v_mfma_f32_16x16x32_bf16 v[40:43], v[92:95], v[108:111], v[40:43]
	v_mfma_f32_16x16x32_bf16 v[36:39], v[92:95], v[112:115], v[36:39]
	s_add_i32 s12, s11, 0xc00
	s_mov_b32 m0, s12
	s_nop 0
	global_load_lds_dwordx4 v[166:167], off
	v_mfma_f32_16x16x32_bf16 v[32:35], v[92:95], v[116:119], v[32:35]
	v_mfma_f32_16x16x32_bf16 v[28:31], v[96:99], v[104:107], v[28:31]
	s_add_i32 s12, s11, 0x4000
	s_mov_b32 m0, s12
	s_nop 0
	global_load_lds_dwordx4 v[154:155], off
	v_mfma_f32_16x16x32_bf16 v[24:27], v[96:99], v[108:111], v[24:27]
	v_mfma_f32_16x16x32_bf16 v[20:23], v[96:99], v[112:115], v[20:23]
	s_add_i32 s12, s11, 0x4400
	s_mov_b32 m0, s12
	s_nop 0
	global_load_lds_dwordx4 v[158:159], off
	v_mfma_f32_16x16x32_bf16 v[16:19], v[96:99], v[116:119], v[16:19]
	v_mfma_f32_16x16x32_bf16 v[12:15], v[100:103], v[104:107], v[12:15]
	s_add_i32 s12, s11, 0x4800
	s_mov_b32 m0, s12
	s_nop 0
	global_load_lds_dwordx4 v[152:153], off
	v_mfma_f32_16x16x32_bf16 v[8:11], v[100:103], v[108:111], v[8:11]
	v_mfma_f32_16x16x32_bf16 v[4:7], v[100:103], v[112:115], v[4:7]
	s_addk_i32 s11, 0x4c00
	s_mov_b32 m0, s11
	s_nop 0
	global_load_lds_dwordx4 v[170:171], off
	v_mfma_f32_16x16x32_bf16 v[0:3], v[100:103], v[116:119], v[0:3]
	s_waitcnt lgkmcnt(3)
	v_mfma_f32_16x16x32_bf16 v[60:63], v[120:123], v[136:139], v[60:63]
	s_waitcnt lgkmcnt(2)
	v_mfma_f32_16x16x32_bf16 v[56:59], v[120:123], v[140:143], v[56:59]
	s_waitcnt lgkmcnt(1)
	v_mfma_f32_16x16x32_bf16 v[52:55], v[120:123], v[144:147], v[52:55]
	s_waitcnt lgkmcnt(0)
	v_mfma_f32_16x16x32_bf16 v[48:51], v[120:123], v[148:151], v[48:51]
	v_mfma_f32_16x16x32_bf16 v[44:47], v[124:127], v[136:139], v[44:47]
	v_mfma_f32_16x16x32_bf16 v[40:43], v[124:127], v[140:143], v[40:43]
	v_mfma_f32_16x16x32_bf16 v[36:39], v[124:127], v[144:147], v[36:39]
	v_mfma_f32_16x16x32_bf16 v[32:35], v[124:127], v[148:151], v[32:35]
	v_mfma_f32_16x16x32_bf16 v[28:31], v[128:131], v[136:139], v[28:31]
	v_mfma_f32_16x16x32_bf16 v[24:27], v[128:131], v[140:143], v[24:27]
	v_mfma_f32_16x16x32_bf16 v[20:23], v[128:131], v[144:147], v[20:23]
	v_mfma_f32_16x16x32_bf16 v[16:19], v[128:131], v[148:151], v[16:19]
	v_mfma_f32_16x16x32_bf16 v[12:15], v[132:135], v[136:139], v[12:15]
	v_mfma_f32_16x16x32_bf16 v[8:11], v[132:135], v[140:143], v[8:11]
	v_mfma_f32_16x16x32_bf16 v[4:7], v[132:135], v[144:147], v[4:7]
	v_mfma_f32_16x16x32_bf16 v[0:3], v[132:135], v[148:151], v[0:3]
	s_setprio 0
	s_add_i32 s10, s10, 0x8000
	s_add_u32 s0, s0, 0x80
	s_addc_u32 s1, s1, 0
	s_addk_i32 s9, 0x4000
	s_cmpk_lg_i32 s0, 0x1580
	s_cbranch_scc1 .LBB0_37
	v_lshlrev_b32_e32 v86, 1, v86
	v_lshlrev_b32_e32 v85, 1, v85
	s_waitcnt vmcnt(0) lgkmcnt(0)
	s_barrier
;     ...
;     asm volatile("s_waitcnt vmcnt(0) lgkmcnt(0)" ::: "memory");
;     __builtin_amdgcn_s_barrier();
;     asm volatile("" ::: "memory");
;     G3_STEP(nk - 1, false)
; DI void resid_tile(const u16* A, int K, const u16* Bt, const float* resid, float* out, int it, u16* sA, u16* sB) {
;     ...
;   float* sC = (float*)sA + w * (32 * 68);
; #pragma unroll
;   for (int hp = 0; hp < 2; ++hp) {
;     __syncthreads();
; #pragma unroll
;     for (int mi2 = 0; mi2 < 2; ++mi2)
; #pragma unroll
;       for (int ni = 0; ni < 4; ++ni)
; #pragma unroll
;         for (int j = 0; j < 4; ++j) sC[(16 * mi2 + 4 * quad + j) * 68 + 16 * ni + r16] = acc[2 * hp + mi2][ni][j];
;     __syncthreads();
; #pragma unroll
;     for (int q = 0; q < 8; ++q) {
;       const int c = lane + 64 * q, row = c >> 4, c4 = (c & 15) * 4;
;       const long o = ((long)mt * 128 + wm * 64 + 32 * hp + row) * DM + nt * 128 + wn * 64 + c4;
;       const float4 rv = *(const float4*)(resid + o);
;       const f32x4 cv = *(const f32x4*)(sC + row * 68 + c4);
;       *(float4*)(out + o) = make_float4(rv.x + cv[0], rv.y + cv[1], rv.z + cv[2], rv.w + cv[3]);
	v_add3_u32 v76, v86, v84, v83
	v_add3_u32 v98, v86, v82, v83
	v_add3_u32 v84, v85, v84, v83
	v_add3_u32 v126, v85, v82, v83
	ds_read_b128 v[64:67], v76 offset:32768
	ds_read_b128 v[68:71], v76 offset:34816
	ds_read_b128 v[72:75], v76 offset:36864
	ds_read_b128 v[76:79], v76 offset:38912
	ds_read_b128 v[86:89], v98 offset:49152
	ds_read_b128 v[90:93], v98 offset:51200
	ds_read_b128 v[94:97], v98 offset:53248
	ds_read_b128 v[98:101], v98 offset:55296
	ds_read_b128 v[102:105], v84 offset:32768
	ds_read_b128 v[106:109], v84 offset:34816
	ds_read_b128 v[110:113], v84 offset:36864
	ds_read_b128 v[114:117], v84 offset:38912
	ds_read_b128 v[82:85], v126 offset:49152
	ds_read_b128 v[118:121], v126 offset:51200
	ds_read_b128 v[122:125], v126 offset:53248
	ds_read_b128 v[126:129], v126 offset:55296
	s_lshl_b64 s[0:1], s[2:3], 7
	v_and_b32_e32 v130, 15, v80
	s_setprio 1
	s_waitcnt lgkmcnt(11)
	v_mfma_f32_16x16x32_bf16 v[60:63], v[64:67], v[86:89], v[60:63]
	s_waitcnt lgkmcnt(10)
	v_mfma_f32_16x16x32_bf16 v[56:59], v[64:67], v[90:93], v[56:59]
	s_waitcnt lgkmcnt(9)
	v_mfma_f32_16x16x32_bf16 v[52:55], v[64:67], v[94:97], v[52:55]
	s_waitcnt lgkmcnt(8)
	v_mfma_f32_16x16x32_bf16 v[48:51], v[64:67], v[98:101], v[48:51]
	v_mfma_f32_16x16x32_bf16 v[44:47], v[68:71], v[86:89], v[44:47]
	v_mfma_f32_16x16x32_bf16 v[40:43], v[68:71], v[90:93], v[40:43]
	v_mfma_f32_16x16x32_bf16 v[36:39], v[68:71], v[94:97], v[36:39]
	v_mfma_f32_16x16x32_bf16 v[32:35], v[68:71], v[98:101], v[32:35]
	v_mfma_f32_16x16x32_bf16 v[28:31], v[72:75], v[86:89], v[28:31]
	v_mfma_f32_16x16x32_bf16 v[64:67], v[72:75], v[90:93], v[24:27]
	v_mfma_f32_16x16x32_bf16 v[20:23], v[72:75], v[94:97], v[20:23]
	v_mfma_f32_16x16x32_bf16 v[68:71], v[72:75], v[98:101], v[16:19]
	v_mfma_f32_16x16x32_bf16 v[12:15], v[76:79], v[86:89], v[12:15]
	v_mfma_f32_16x16x32_bf16 v[72:75], v[76:79], v[90:93], v[8:11]
	v_mfma_f32_16x16x32_bf16 v[4:7], v[76:79], v[94:97], v[4:7]
	v_mfma_f32_16x16x32_bf16 v[76:79], v[76:79], v[98:101], v[0:3]
	s_waitcnt lgkmcnt(3)
	v_mfma_f32_16x16x32_bf16 v[60:63], v[102:105], v[82:85], v[60:63]
	s_waitcnt lgkmcnt(2)
	v_mfma_f32_16x16x32_bf16 v[56:59], v[102:105], v[118:121], v[56:59]
	s_waitcnt lgkmcnt(1)
	v_mfma_f32_16x16x32_bf16 v[52:55], v[102:105], v[122:125], v[52:55]
	s_waitcnt lgkmcnt(0)
	v_mfma_f32_16x16x32_bf16 v[48:51], v[102:105], v[126:129], v[48:51]
	v_mfma_f32_16x16x32_bf16 v[44:47], v[106:109], v[82:85], v[44:47]
	v_mfma_f32_16x16x32_bf16 v[40:43], v[106:109], v[118:121], v[40:43]
	v_mfma_f32_16x16x32_bf16 v[36:39], v[106:109], v[122:125], v[36:39]
	v_mfma_f32_16x16x32_bf16 v[86:89], v[106:109], v[126:129], v[32:35]
	v_mfma_f32_16x16x32_bf16 v[24:27], v[110:113], v[82:85], v[28:31]
	v_mfma_f32_16x16x32_bf16 v[28:31], v[110:113], v[118:121], v[64:67]
	v_mfma_f32_16x16x32_bf16 v[16:19], v[110:113], v[122:125], v[20:23]
	v_mfma_f32_16x16x32_bf16 v[20:23], v[110:113], v[126:129], v[68:71]
	v_mfma_f32_16x16x32_bf16 v[8:11], v[114:117], v[82:85], v[12:15]
	v_mfma_f32_16x16x32_bf16 v[12:15], v[114:117], v[118:121], v[72:75]
	v_mfma_f32_16x16x32_bf16 v[0:3], v[114:117], v[122:125], v[4:7]
	v_mfma_f32_16x16x32_bf16 v[4:7], v[114:117], v[126:129], v[76:79]
	s_setprio 0
	v_lshrrev_b32_e32 v32, 2, v80
	v_and_b32_e32 v65, 12, v32
	v_lshlrev_b32_e32 v32, 2, v80
	v_and_b32_e32 v67, 60, v32
	v_ashrrev_i32_e32 v32, 1, v80
	v_and_b32_e32 v32, 0xffffffc0, v32
	v_ashrrev_i32_e32 v33, 31, v32
	v_mul_lo_u32 v64, v81, s18
	v_lshl_add_u64 v[32:33], s[0:1], 0, v[32:33]
	s_lshl_b32 s0, s7, 7
	v_and_b32_e32 v34, 64, v80
	v_lshl_or_b32 v66, v130, 2, v64
	s_ashr_i32 s1, s0, 31
	v_or3_b32 v34, s0, v34, v67
	s_movk_i32 s0, 0x110
	v_mad_u32_u24 v65, v65, s0, v66
	v_lshl_or_b32 v64, v67, 2, v64
	v_bfe_u32 v67, v80, 4, 2
	v_lshlrev_b32_e32 v175, 2, v34
	v_or3_b32 v174, v32, v67, 0
	v_lshl_add_u32 v90, v174, 12, v175
	global_load_dwordx4 v[106:109], v90, s[68:69]
	v_or3_b32 v174, v32, v67, 4
	v_lshl_add_u32 v91, v174, 12, v175
	global_load_dwordx4 v[110:113], v91, s[68:69]
	v_or3_b32 v174, v32, v67, 8
	v_lshl_add_u32 v92, v174, 12, v175
	global_load_dwordx4 v[114:117], v92, s[68:69]
	v_or3_b32 v174, v32, v67, 12
	v_lshl_add_u32 v93, v174, 12, v175
	global_load_dwordx4 v[118:121], v93, s[68:69]
	v_or3_b32 v174, v32, v67, 16
	v_lshl_add_u32 v94, v174, 12, v175
	global_load_dwordx4 v[122:125], v94, s[68:69]
	v_or3_b32 v174, v32, v67, 20
	v_lshl_add_u32 v95, v174, 12, v175
	global_load_dwordx4 v[126:129], v95, s[68:69]
	v_or3_b32 v174, v32, v67, 24
	v_lshl_add_u32 v96, v174, 12, v175
	global_load_dwordx4 v[130:133], v96, s[68:69]
	v_or3_b32 v174, v32, v67, 28
	v_lshl_add_u32 v97, v174, 12, v175
	global_load_dwordx4 v[134:137], v97, s[68:69]
	v_or3_b32 v174, v32, v67, 32
	v_lshl_add_u32 v98, v174, 12, v175
	global_load_dwordx4 v[210:213], v98, s[68:69]
	v_or3_b32 v174, v32, v67, 36
	v_lshl_add_u32 v99, v174, 12, v175
	global_load_dwordx4 v[214:217], v99, s[68:69]
	v_or3_b32 v174, v32, v67, 40
	v_lshl_add_u32 v100, v174, 12, v175
	global_load_dwordx4 v[218:221], v100, s[68:69]
	v_or3_b32 v174, v32, v67, 44
	v_lshl_add_u32 v101, v174, 12, v175
	global_load_dwordx4 v[222:225], v101, s[68:69]
	v_or3_b32 v174, v32, v67, 48
	v_lshl_add_u32 v102, v174, 12, v175
	global_load_dwordx4 v[226:229], v102, s[68:69]
	v_or3_b32 v174, v32, v67, 52
	v_lshl_add_u32 v103, v174, 12, v175
	global_load_dwordx4 v[230:233], v103, s[68:69]
	v_or3_b32 v174, v32, v67, 56
	v_lshl_add_u32 v104, v174, 12, v175
	global_load_dwordx4 v[234:237], v104, s[68:69]
	v_or3_b32 v174, v32, v67, 60
	v_lshl_add_u32 v105, v174, 12, v175
	global_load_dwordx4 v[238:241], v105, s[68:69]
	s_barrier
; DI void resid_tile(const u16* A, int K, const u16* Bt, const float* resid, float* out, int it, u16* sA, u16* sB) {
;     ...
;   float* sC = (float*)sA + w * (32 * 68);
; #pragma unroll
;   for (int hp = 0; hp < 2; ++hp) {
;     __syncthreads();
; #pragma unroll
;     for (int mi2 = 0; mi2 < 2; ++mi2)
; #pragma unroll
;       for (int ni = 0; ni < 4; ++ni)
; #pragma unroll
;         for (int j = 0; j < 4; ++j) sC[(16 * mi2 + 4 * quad + j) * 68 + 16 * ni + r16] = acc[2 * hp + mi2][ni][j];
;     __syncthreads();
; #pragma unroll
;     for (int q = 0; q < 8; ++q) {
;       const int c = lane + 64 * q, row = c >> 4, c4 = (c & 15) * 4;
;       const long o = ((long)mt * 128 + wm * 64 + 32 * hp + row) * DM + nt * 128 + wn * 64 + c4;
;       const float4 rv = *(const float4*)(resid + o);
;       const f32x4 cv = *(const f32x4*)(sC + row * 68 + c4);
;       *(float4*)(out + o) = make_float4(rv.x + cv[0], rv.y + cv[1], rv.z + cv[2], rv.w + cv[3]);
;     }
;   }
	ds_write2_b32 v65, v60, v56 offset1:16
	ds_write2_b32 v65, v61, v57 offset0:68 offset1:84
	ds_write2_b32 v65, v62, v58 offset0:136 offset1:152
	ds_write2_b32 v65, v63, v59 offset0:204 offset1:220
	ds_write2_b32 v65, v52, v48 offset0:32 offset1:48
	ds_write2_b32 v65, v53, v49 offset0:100 offset1:116
	ds_write2_b32 v65, v54, v50 offset0:168 offset1:184
	ds_write2_b32 v65, v55, v51 offset0:236 offset1:252
	v_add_u32_e32 v48, 0x1000, v65
	v_add_u32_e32 v49, 0x1400, v65
	ds_write2_b32 v48, v44, v40 offset0:64 offset1:80
	ds_write2_b32 v48, v45, v41 offset0:132 offset1:148
	ds_write2_b32 v48, v46, v42 offset0:200 offset1:216
	ds_write2_b32 v49, v47, v43 offset0:12 offset1:28
	ds_write2_b32 v48, v36, v86 offset0:96 offset1:112
	ds_write2_b32 v48, v37, v87 offset0:164 offset1:180
	ds_write2_b32 v48, v38, v88 offset0:232 offset1:248
	ds_write2_b32 v49, v39, v89 offset0:44 offset1:60
	s_waitcnt lgkmcnt(0)
	s_barrier
	v_mad_u32_u24 v36, v67, s0, v64
	ds_read_b128 v[40:43], v36
	ds_read_b128 v[44:47], v36 offset:1088
	ds_read_b128 v[52:55], v36 offset:2176
	ds_read_b128 v[56:59], v36 offset:3264
	ds_read_b128 v[60:63], v36 offset:4352
	ds_read_b128 v[68:71], v36 offset:5440
	ds_read_b128 v[72:75], v36 offset:6528
	ds_read_b128 v[76:79], v36 offset:7616
	s_add_i32 s4, s4, s6
	s_cmp_lt_i32 s4, s5
	s_waitcnt vmcnt(8) lgkmcnt(0)
	v_pk_add_f32 v[40:41], v[106:107], v[40:41]
	v_pk_add_f32 v[42:43], v[108:109], v[42:43]
	global_store_dwordx4 v90, v[40:43], s[68:69]
	v_pk_add_f32 v[44:45], v[110:111], v[44:45]
	v_pk_add_f32 v[46:47], v[112:113], v[46:47]
	global_store_dwordx4 v91, v[44:47], s[68:69]
	v_pk_add_f32 v[52:53], v[114:115], v[52:53]
	v_pk_add_f32 v[54:55], v[116:117], v[54:55]
	global_store_dwordx4 v92, v[52:55], s[68:69]
	v_pk_add_f32 v[56:57], v[118:119], v[56:57]
	v_pk_add_f32 v[58:59], v[120:121], v[58:59]
	global_store_dwordx4 v93, v[56:59], s[68:69]
	v_pk_add_f32 v[60:61], v[122:123], v[60:61]
	v_pk_add_f32 v[62:63], v[124:125], v[62:63]
	global_store_dwordx4 v94, v[60:63], s[68:69]
	v_pk_add_f32 v[68:69], v[126:127], v[68:69]
	v_pk_add_f32 v[70:71], v[128:129], v[70:71]
	global_store_dwordx4 v95, v[68:71], s[68:69]
	v_pk_add_f32 v[72:73], v[130:131], v[72:73]
	v_pk_add_f32 v[74:75], v[132:133], v[74:75]
	global_store_dwordx4 v96, v[72:75], s[68:69]
	v_pk_add_f32 v[76:77], v[134:135], v[76:77]
	v_pk_add_f32 v[78:79], v[136:137], v[78:79]
	global_store_dwordx4 v97, v[76:79], s[68:69]
	s_barrier
	ds_write2_b32 v65, v24, v28 offset1:16
	ds_write2_b32 v65, v25, v29 offset0:68 offset1:84
	ds_write2_b32 v65, v26, v30 offset0:136 offset1:152
	ds_write2_b32 v65, v27, v31 offset0:204 offset1:220
	ds_write2_b32 v65, v16, v20 offset0:32 offset1:48
	ds_write2_b32 v65, v17, v21 offset0:100 offset1:116
	ds_write2_b32 v65, v18, v22 offset0:168 offset1:184
	ds_write2_b32 v65, v19, v23 offset0:236 offset1:252
	ds_write2_b32 v48, v8, v12 offset0:64 offset1:80
	ds_write2_b32 v48, v9, v13 offset0:132 offset1:148
	ds_write2_b32 v48, v10, v14 offset0:200 offset1:216
	ds_write2_b32 v49, v11, v15 offset0:12 offset1:28
	ds_write2_b32 v48, v0, v4 offset0:96 offset1:112
	ds_write2_b32 v48, v1, v5 offset0:164 offset1:180
	ds_write2_b32 v48, v2, v6 offset0:232 offset1:248
	ds_write2_b32 v49, v3, v7 offset0:44 offset1:60
	s_waitcnt lgkmcnt(0)
	s_barrier
	ds_read_b128 v[0:3], v36
	ds_read_b128 v[4:7], v36 offset:1088
	ds_read_b128 v[8:11], v36 offset:2176
	ds_read_b128 v[12:15], v36 offset:3264
	ds_read_b128 v[16:19], v36 offset:4352
	ds_read_b128 v[20:23], v36 offset:5440
	ds_read_b128 v[24:27], v36 offset:6528
	ds_read_b128 v[28:31], v36 offset:7616
	s_waitcnt vmcnt(8) lgkmcnt(0)
	v_pk_add_f32 v[0:1], v[210:211], v[0:1]
	v_pk_add_f32 v[2:3], v[212:213], v[2:3]
	global_store_dwordx4 v98, v[0:3], s[68:69]
	v_pk_add_f32 v[4:5], v[214:215], v[4:5]
	v_pk_add_f32 v[6:7], v[216:217], v[6:7]
	global_store_dwordx4 v99, v[4:7], s[68:69]
	v_pk_add_f32 v[8:9], v[218:219], v[8:9]
	v_pk_add_f32 v[10:11], v[220:221], v[10:11]
	global_store_dwordx4 v100, v[8:11], s[68:69]
	v_pk_add_f32 v[12:13], v[222:223], v[12:13]
	v_pk_add_f32 v[14:15], v[224:225], v[14:15]
	global_store_dwordx4 v101, v[12:15], s[68:69]
	v_pk_add_f32 v[16:17], v[226:227], v[16:17]
	v_pk_add_f32 v[18:19], v[228:229], v[18:19]
	global_store_dwordx4 v102, v[16:19], s[68:69]
	v_pk_add_f32 v[20:21], v[230:231], v[20:21]
	v_pk_add_f32 v[22:23], v[232:233], v[22:23]
	global_store_dwordx4 v103, v[20:23], s[68:69]
	v_pk_add_f32 v[24:25], v[234:235], v[24:25]
	v_pk_add_f32 v[26:27], v[236:237], v[26:27]
	global_store_dwordx4 v104, v[24:27], s[68:69]
	v_pk_add_f32 v[28:29], v[238:239], v[28:29]
	v_pk_add_f32 v[30:31], v[240:241], v[30:31]
	global_store_dwordx4 v105, v[28:31], s[68:69]
	s_cbranch_scc1 .LBB0_36

;     ...
; #pragma unroll 1
;     for (int kt = 0; kt < nk - 1; ++kt) {
;       asm volatile("s_waitcnt vmcnt(0) lgkmcnt(0)" ::: "memory");
;       __builtin_amdgcn_s_barrier();
;       asm volatile("" ::: "memory");
;       G3_STEP(kt, true)
;     }
.LBB0_107:
	s_lshl_b32 s11, s9, 1
	s_and_b32 s11, s11, 0x8000
	v_lshl_or_b32 v87, v86, 1, s11
	s_waitcnt vmcnt(0) lgkmcnt(0)
	s_barrier
	v_add3_u32 v100, v87, v84, v83
	v_add3_u32 v87, v87, v82, v83
	ds_read_b128 v[88:91], v100
	ds_read_b128 v[92:95], v100 offset:2048
	ds_read_b128 v[96:99], v100 offset:4096
	ds_read_b128 v[100:103], v100 offset:6144
	ds_read_b128 v[104:107], v87 offset:16384
	ds_read_b128 v[108:111], v87 offset:18432
	ds_read_b128 v[112:115], v87 offset:20480
	ds_read_b128 v[116:119], v87 offset:22528
	v_lshl_or_b32 v87, v85, 1, s11
	v_add3_u32 v132, v87, v84, v83
	v_add3_u32 v87, v87, v82, v83
	ds_read_b128 v[120:123], v132
	ds_read_b128 v[124:127], v132 offset:2048
	ds_read_b128 v[128:131], v132 offset:4096
	ds_read_b128 v[132:135], v132 offset:6144
	ds_read_b128 v[136:139], v87 offset:16384
	ds_read_b128 v[140:143], v87 offset:18432
	ds_read_b128 v[144:147], v87 offset:20480
	ds_read_b128 v[148:151], v87 offset:22528
	s_setprio 1
	s_andn2_b32 s11, 0x8000, s10
	s_waitcnt lgkmcnt(11)
	v_mfma_f32_16x16x32_bf16 v[60:63], v[88:91], v[104:107], v[60:63]
	s_add_i32 s11, s1, s11
	v_lshl_add_u64 v[172:173], v[64:65], 0, s[2:3]
	s_mov_b32 m0, s11
	s_nop 0
	global_load_lds_dwordx4 v[172:173], off
	s_waitcnt lgkmcnt(10)
	v_mfma_f32_16x16x32_bf16 v[56:59], v[88:91], v[108:111], v[56:59]
	v_lshl_add_u64 v[152:153], v[78:79], 0, s[2:3]
	v_lshl_add_u64 v[154:155], v[76:77], 0, s[2:3]
	v_lshl_add_u64 v[156:157], v[74:75], 0, s[2:3]
	v_lshl_add_u64 v[158:159], v[72:73], 0, s[2:3]
	v_lshl_add_u64 v[166:167], v[70:71], 0, s[2:3]
	v_lshl_add_u64 v[168:169], v[68:69], 0, s[2:3]
	v_lshl_add_u64 v[170:171], v[66:67], 0, s[2:3]
	s_waitcnt lgkmcnt(9)
	v_mfma_f32_16x16x32_bf16 v[52:55], v[88:91], v[112:115], v[52:55]
	s_add_i32 s12, s11, 0x400
	s_mov_b32 m0, s12
	s_nop 0
	global_load_lds_dwordx4 v[168:169], off
	s_waitcnt lgkmcnt(8)
	v_mfma_f32_16x16x32_bf16 v[48:51], v[88:91], v[116:119], v[48:51]
	v_mfma_f32_16x16x32_bf16 v[44:47], v[92:95], v[104:107], v[44:47]
	s_add_i32 s12, s11, 0x800
	s_mov_b32 m0, s12
	s_nop 0
	global_load_lds_dwordx4 v[156:157], off
	v_mfma_f32_16x16x32_bf16 v[40:43], v[92:95], v[108:111], v[40:43]
	v_mfma_f32_16x16x32_bf16 v[36:39], v[92:95], v[112:115], v[36:39]
	s_add_i32 s12, s11, 0xc00
	s_mov_b32 m0, s12
	s_nop 0
	global_load_lds_dwordx4 v[166:167], off
	v_mfma_f32_16x16x32_bf16 v[32:35], v[92:95], v[116:119], v[32:35]
	v_mfma_f32_16x16x32_bf16 v[28:31], v[96:99], v[104:107], v[28:31]
	s_add_i32 s12, s11, 0x4000
	s_mov_b32 m0, s12
	s_nop 0
	global_load_lds_dwordx4 v[154:155], off
	v_mfma_f32_16x16x32_bf16 v[24:27], v[96:99], v[108:111], v[24:27]
	v_mfma_f32_16x16x32_bf16 v[20:23], v[96:99], v[112:115], v[20:23]
	s_add_i32 s12, s11, 0x4400
	s_mov_b32 m0, s12
	s_nop 0
	global_load_lds_dwordx4 v[158:159], off
	v_mfma_f32_16x16x32_bf16 v[16:19], v[96:99], v[116:119], v[16:19]
	v_mfma_f32_16x16x32_bf16 v[12:15], v[100:103], v[104:107], v[12:15]
	s_add_i32 s12, s11, 0x4800
	s_mov_b32 m0, s12
	s_nop 0
	global_load_lds_dwordx4 v[152:153], off
	v_mfma_f32_16x16x32_bf16 v[8:11], v[100:103], v[108:111], v[8:11]
	v_mfma_f32_16x16x32_bf16 v[4:7], v[100:103], v[112:115], v[4:7]
	s_addk_i32 s11, 0x4c00
	s_mov_b32 m0, s11
	s_nop 0
	global_load_lds_dwordx4 v[170:171], off
	v_mfma_f32_16x16x32_bf16 v[0:3], v[100:103], v[116:119], v[0:3]
	s_waitcnt lgkmcnt(3)
	v_mfma_f32_16x16x32_bf16 v[60:63], v[120:123], v[136:139], v[60:63]
	s_waitcnt lgkmcnt(2)
	v_mfma_f32_16x16x32_bf16 v[56:59], v[120:123], v[140:143], v[56:59]
	s_waitcnt lgkmcnt(1)
	v_mfma_f32_16x16x32_bf16 v[52:55], v[120:123], v[144:147], v[52:55]
	s_waitcnt lgkmcnt(0)
	v_mfma_f32_16x16x32_bf16 v[48:51], v[120:123], v[148:151], v[48:51]
	v_mfma_f32_16x16x32_bf16 v[44:47], v[124:127], v[136:139], v[44:47]
	v_mfma_f32_16x16x32_bf16 v[40:43], v[124:127], v[140:143], v[40:43]
	v_mfma_f32_16x16x32_bf16 v[36:39], v[124:127], v[144:147], v[36:39]
	v_mfma_f32_16x16x32_bf16 v[32:35], v[124:127], v[148:151], v[32:35]
	v_mfma_f32_16x16x32_bf16 v[28:31], v[128:131], v[136:139], v[28:31]
	v_mfma_f32_16x16x32_bf16 v[24:27], v[128:131], v[140:143], v[24:27]
	v_mfma_f32_16x16x32_bf16 v[20:23], v[128:131], v[144:147], v[20:23]
	v_mfma_f32_16x16x32_bf16 v[16:19], v[128:131], v[148:151], v[16:19]
	v_mfma_f32_16x16x32_bf16 v[12:15], v[132:135], v[136:139], v[12:15]
	v_mfma_f32_16x16x32_bf16 v[8:11], v[132:135], v[140:143], v[8:11]
	v_mfma_f32_16x16x32_bf16 v[4:7], v[132:135], v[144:147], v[4:7]
	v_mfma_f32_16x16x32_bf16 v[0:3], v[132:135], v[148:151], v[0:3]
	s_setprio 0
	s_add_i32 s10, s10, 0x8000
	s_add_u32 s2, s2, 0x80
	s_addc_u32 s3, s3, 0
	s_addk_i32 s9, 0x4000
	s_cmpk_lg_i32 s2, 0x780
	s_cbranch_scc1 .LBB0_107
	v_lshlrev_b32_e32 v86, 1, v86
	v_lshlrev_b32_e32 v85, 1, v85
	s_waitcnt vmcnt(0) lgkmcnt(0)
	s_barrier
; DI void resid_tile(const u16* A, int K, const u16* Bt, const float* resid, float* out, int it, u16* sA, u16* sB) {
;     ...
;   float* sC = (float*)sA + w * (32 * 68);
; #pragma unroll
;   for (int hp = 0; hp < 2; ++hp) {
;     __syncthreads();
; #pragma unroll
;     for (int mi2 = 0; mi2 < 2; ++mi2)
; #pragma unroll
;       for (int ni = 0; ni < 4; ++ni)
; #pragma unroll
;         for (int j = 0; j < 4; ++j) sC[(16 * mi2 + 4 * quad + j) * 68 + 16 * ni + r16] = acc[2 * hp + mi2][ni][j];
;     __syncthreads();
; #pragma unroll
;     for (int q = 0; q < 8; ++q) {
;       const int c = lane + 64 * q, row = c >> 4, c4 = (c & 15) * 4;
;       const long o = ((long)mt * 128 + wm * 64 + 32 * hp + row) * DM + nt * 128 + wn * 64 + c4;
;       const float4 rv = *(const float4*)(resid + o);
;       const f32x4 cv = *(const f32x4*)(sC + row * 68 + c4);
;       *(float4*)(out + o) = make_float4(rv.x + cv[0], rv.y + cv[1], rv.z + cv[2], rv.w + cv[3]);
	v_add3_u32 v76, v86, v84, v83
	v_add3_u32 v98, v86, v82, v83
	v_add3_u32 v84, v85, v84, v83
	v_add3_u32 v126, v85, v82, v83
	ds_read_b128 v[64:67], v76 offset:32768
	ds_read_b128 v[68:71], v76 offset:34816
	ds_read_b128 v[72:75], v76 offset:36864
	ds_read_b128 v[76:79], v76 offset:38912
	ds_read_b128 v[86:89], v98 offset:49152
	ds_read_b128 v[90:93], v98 offset:51200
	ds_read_b128 v[94:97], v98 offset:53248
	ds_read_b128 v[98:101], v98 offset:55296
	ds_read_b128 v[102:105], v84 offset:32768
	ds_read_b128 v[106:109], v84 offset:34816
	ds_read_b128 v[110:113], v84 offset:36864
	ds_read_b128 v[114:117], v84 offset:38912
	ds_read_b128 v[82:85], v126 offset:49152
	ds_read_b128 v[118:121], v126 offset:51200
	ds_read_b128 v[122:125], v126 offset:53248
	ds_read_b128 v[126:129], v126 offset:55296
	s_lshl_b64 s[2:3], s[4:5], 7
	v_and_b32_e32 v130, 15, v80
	s_setprio 1
	s_waitcnt lgkmcnt(11)
	v_mfma_f32_16x16x32_bf16 v[60:63], v[64:67], v[86:89], v[60:63]
	s_waitcnt lgkmcnt(10)
	v_mfma_f32_16x16x32_bf16 v[56:59], v[64:67], v[90:93], v[56:59]
	s_waitcnt lgkmcnt(9)
	v_mfma_f32_16x16x32_bf16 v[52:55], v[64:67], v[94:97], v[52:55]
	s_waitcnt lgkmcnt(8)
	v_mfma_f32_16x16x32_bf16 v[48:51], v[64:67], v[98:101], v[48:51]
	v_mfma_f32_16x16x32_bf16 v[44:47], v[68:71], v[86:89], v[44:47]
	v_mfma_f32_16x16x32_bf16 v[40:43], v[68:71], v[90:93], v[40:43]
	v_mfma_f32_16x16x32_bf16 v[36:39], v[68:71], v[94:97], v[36:39]
	v_mfma_f32_16x16x32_bf16 v[32:35], v[68:71], v[98:101], v[32:35]
	v_mfma_f32_16x16x32_bf16 v[28:31], v[72:75], v[86:89], v[28:31]
	v_mfma_f32_16x16x32_bf16 v[64:67], v[72:75], v[90:93], v[24:27]
	v_mfma_f32_16x16x32_bf16 v[20:23], v[72:75], v[94:97], v[20:23]
	v_mfma_f32_16x16x32_bf16 v[68:71], v[72:75], v[98:101], v[16:19]
	v_mfma_f32_16x16x32_bf16 v[12:15], v[76:79], v[86:89], v[12:15]
	v_mfma_f32_16x16x32_bf16 v[72:75], v[76:79], v[90:93], v[8:11]
	v_mfma_f32_16x16x32_bf16 v[4:7], v[76:79], v[94:97], v[4:7]
	v_mfma_f32_16x16x32_bf16 v[76:79], v[76:79], v[98:101], v[0:3]
	s_waitcnt lgkmcnt(3)
	v_mfma_f32_16x16x32_bf16 v[60:63], v[102:105], v[82:85], v[60:63]
	s_waitcnt lgkmcnt(2)
	v_mfma_f32_16x16x32_bf16 v[56:59], v[102:105], v[118:121], v[56:59]
	s_waitcnt lgkmcnt(1)
	v_mfma_f32_16x16x32_bf16 v[52:55], v[102:105], v[122:125], v[52:55]
	s_waitcnt lgkmcnt(0)
	v_mfma_f32_16x16x32_bf16 v[48:51], v[102:105], v[126:129], v[48:51]
	v_mfma_f32_16x16x32_bf16 v[44:47], v[106:109], v[82:85], v[44:47]
	v_mfma_f32_16x16x32_bf16 v[40:43], v[106:109], v[118:121], v[40:43]
	v_mfma_f32_16x16x32_bf16 v[36:39], v[106:109], v[122:125], v[36:39]
	v_mfma_f32_16x16x32_bf16 v[86:89], v[106:109], v[126:129], v[32:35]
	v_mfma_f32_16x16x32_bf16 v[24:27], v[110:113], v[82:85], v[28:31]
	v_mfma_f32_16x16x32_bf16 v[28:31], v[110:113], v[118:121], v[64:67]
	v_mfma_f32_16x16x32_bf16 v[16:19], v[110:113], v[122:125], v[20:23]
	v_mfma_f32_16x16x32_bf16 v[20:23], v[110:113], v[126:129], v[68:71]
	v_mfma_f32_16x16x32_bf16 v[8:11], v[114:117], v[82:85], v[12:15]
	v_mfma_f32_16x16x32_bf16 v[12:15], v[114:117], v[118:121], v[72:75]
	v_mfma_f32_16x16x32_bf16 v[0:3], v[114:117], v[122:125], v[4:7]
	v_mfma_f32_16x16x32_bf16 v[4:7], v[114:117], v[126:129], v[76:79]
	s_setprio 0
	v_lshrrev_b32_e32 v32, 2, v80
	v_and_b32_e32 v65, 12, v32
	v_lshlrev_b32_e32 v32, 2, v80
	v_mul_lo_u32 v64, v81, s16
	v_and_b32_e32 v67, 60, v32
	v_ashrrev_i32_e32 v32, 1, v80
	s_lshl_b32 s0, s0, 7
	v_and_b32_e32 v34, 64, v80
	v_lshl_or_b32 v66, v130, 2, v64
	v_and_b32_e32 v32, 0xffffffc0, v32
	s_ashr_i32 s1, s0, 31
	v_or3_b32 v34, s0, v34, v67
	s_movk_i32 s0, 0x110
	v_ashrrev_i32_e32 v33, 31, v32
	v_mad_u32_u24 v65, v65, s0, v66
	v_lshl_add_u64 v[32:33], s[2:3], 0, v[32:33]
	v_bfe_u32 v68, v80, 4, 2
	v_lshlrev_b32_e32 v175, 2, v34
	v_or3_b32 v174, v32, v68, 0
	v_lshl_add_u32 v90, v174, 12, v175
	global_load_dwordx4 v[106:109], v90, s[18:19]
	v_or3_b32 v174, v32, v68, 4
	v_lshl_add_u32 v91, v174, 12, v175
	global_load_dwordx4 v[110:113], v91, s[18:19]
	v_or3_b32 v174, v32, v68, 8
	v_lshl_add_u32 v92, v174, 12, v175
	global_load_dwordx4 v[114:117], v92, s[18:19]
	v_or3_b32 v174, v32, v68, 12
	v_lshl_add_u32 v93, v174, 12, v175
	global_load_dwordx4 v[118:121], v93, s[18:19]
	v_or3_b32 v174, v32, v68, 16
	v_lshl_add_u32 v94, v174, 12, v175
	global_load_dwordx4 v[122:125], v94, s[18:19]
	v_or3_b32 v174, v32, v68, 20
	v_lshl_add_u32 v95, v174, 12, v175
	global_load_dwordx4 v[126:129], v95, s[18:19]
	v_or3_b32 v174, v32, v68, 24
	v_lshl_add_u32 v96, v174, 12, v175
	global_load_dwordx4 v[130:133], v96, s[18:19]
	v_or3_b32 v174, v32, v68, 28
	v_lshl_add_u32 v97, v174, 12, v175
	global_load_dwordx4 v[134:137], v97, s[18:19]
	v_or3_b32 v174, v32, v68, 32
	v_lshl_add_u32 v98, v174, 12, v175
	global_load_dwordx4 v[210:213], v98, s[18:19]
	v_or3_b32 v174, v32, v68, 36
	v_lshl_add_u32 v99, v174, 12, v175
	global_load_dwordx4 v[214:217], v99, s[18:19]
	v_or3_b32 v174, v32, v68, 40
	v_lshl_add_u32 v100, v174, 12, v175
	global_load_dwordx4 v[218:221], v100, s[18:19]
	v_or3_b32 v174, v32, v68, 44
	v_lshl_add_u32 v101, v174, 12, v175
	global_load_dwordx4 v[222:225], v101, s[18:19]
	v_or3_b32 v174, v32, v68, 48
	v_lshl_add_u32 v102, v174, 12, v175
	global_load_dwordx4 v[226:229], v102, s[18:19]
	v_or3_b32 v174, v32, v68, 52
	v_lshl_add_u32 v103, v174, 12, v175
	global_load_dwordx4 v[230:233], v103, s[18:19]
	v_or3_b32 v174, v32, v68, 56
	v_lshl_add_u32 v104, v174, 12, v175
	global_load_dwordx4 v[234:237], v104, s[18:19]
	v_or3_b32 v174, v32, v68, 60
	v_lshl_add_u32 v105, v174, 12, v175
	global_load_dwordx4 v[238:241], v105, s[18:19]
	s_barrier
; DI void resid_tile(const u16* A, int K, const u16* Bt, const float* resid, float* out, int it, u16* sA, u16* sB) {
;     ...
;   for (int hp = 0; hp < 2; ++hp) {
;     __syncthreads();
; #pragma unroll
;     for (int mi2 = 0; mi2 < 2; ++mi2)
; #pragma unroll
;       for (int ni = 0; ni < 4; ++ni)
; #pragma unroll
;         for (int j = 0; j < 4; ++j) sC[(16 * mi2 + 4 * quad + j) * 68 + 16 * ni + r16] = acc[2 * hp + mi2][ni][j];
;     __syncthreads();
; #pragma unroll
;     for (int q = 0; q < 8; ++q) {
;       const int c = lane + 64 * q, row = c >> 4, c4 = (c & 15) * 4;
;       const long o = ((long)mt * 128 + wm * 64 + 32 * hp + row) * DM + nt * 128 + wn * 64 + c4;
;       const float4 rv = *(const float4*)(resid + o);
;       const f32x4 cv = *(const f32x4*)(sC + row * 68 + c4);
;       *(float4*)(out + o) = make_float4(rv.x + cv[0], rv.y + cv[1], rv.z + cv[2], rv.w + cv[3]);
;     }
;   }
	ds_write2_b32 v65, v60, v56 offset1:16
	ds_write2_b32 v65, v61, v57 offset0:68 offset1:84
	ds_write2_b32 v65, v62, v58 offset0:136 offset1:152
	ds_write2_b32 v65, v63, v59 offset0:204 offset1:220
	ds_write2_b32 v65, v52, v48 offset0:32 offset1:48
	ds_write2_b32 v65, v53, v49 offset0:100 offset1:116
	ds_write2_b32 v65, v54, v50 offset0:168 offset1:184
	ds_write2_b32 v65, v55, v51 offset0:236 offset1:252
	v_add_u32_e32 v54, 0x1000, v65
	v_add_u32_e32 v55, 0x1400, v65
	ds_write2_b32 v54, v44, v40 offset0:64 offset1:80
	ds_write2_b32 v54, v45, v41 offset0:132 offset1:148
	ds_write2_b32 v54, v46, v42 offset0:200 offset1:216
	ds_write2_b32 v55, v47, v43 offset0:12 offset1:28
	ds_write2_b32 v54, v36, v86 offset0:96 offset1:112
	ds_write2_b32 v54, v37, v87 offset0:164 offset1:180
	ds_write2_b32 v54, v38, v88 offset0:232 offset1:248
	ds_write2_b32 v55, v39, v89 offset0:44 offset1:60
	s_waitcnt lgkmcnt(0)
	s_barrier
	v_lshl_or_b32 v40, v67, 2, v64
	v_mad_u32_u24 v57, v68, s0, v40
	ds_read_b128 v[36:39], v57
	ds_read_b128 v[40:43], v57 offset:1088
	ds_read_b128 v[44:47], v57 offset:2176
	ds_read_b128 v[48:51], v57 offset:3264
	ds_read_b128 v[60:63], v57 offset:4352
	ds_read_b128 v[72:75], v57 offset:5440
	ds_read_b128 v[76:79], v57 offset:6528
	ds_read_b128 v[174:177], v57 offset:7616
	s_add_i32 s6, s6, s8
	s_cmp_ge_i32 s6, s7
	s_waitcnt vmcnt(8) lgkmcnt(0)
	v_pk_add_f32 v[36:37], v[106:107], v[36:37]
	v_pk_add_f32 v[38:39], v[108:109], v[38:39]
	global_store_dwordx4 v90, v[36:39], s[68:69]
	v_pk_add_f32 v[40:41], v[110:111], v[40:41]
	v_pk_add_f32 v[42:43], v[112:113], v[42:43]
	global_store_dwordx4 v91, v[40:43], s[68:69]
	v_pk_add_f32 v[44:45], v[114:115], v[44:45]
	v_pk_add_f32 v[46:47], v[116:117], v[46:47]
	global_store_dwordx4 v92, v[44:47], s[68:69]
	v_pk_add_f32 v[48:49], v[118:119], v[48:49]
	v_pk_add_f32 v[50:51], v[120:121], v[50:51]
	global_store_dwordx4 v93, v[48:51], s[68:69]
	v_pk_add_f32 v[60:61], v[122:123], v[60:61]
	v_pk_add_f32 v[62:63], v[124:125], v[62:63]
	global_store_dwordx4 v94, v[60:63], s[68:69]
	v_pk_add_f32 v[72:73], v[126:127], v[72:73]
	v_pk_add_f32 v[74:75], v[128:129], v[74:75]
	global_store_dwordx4 v95, v[72:75], s[68:69]
	v_pk_add_f32 v[76:77], v[130:131], v[76:77]
	v_pk_add_f32 v[78:79], v[132:133], v[78:79]
	global_store_dwordx4 v96, v[76:79], s[68:69]
	v_pk_add_f32 v[174:175], v[134:135], v[174:175]
	v_pk_add_f32 v[176:177], v[136:137], v[176:177]
	global_store_dwordx4 v97, v[174:177], s[68:69]
	s_barrier
	ds_write2_b32 v65, v24, v28 offset1:16
	ds_write2_b32 v65, v25, v29 offset0:68 offset1:84
	ds_write2_b32 v65, v26, v30 offset0:136 offset1:152
	ds_write2_b32 v65, v27, v31 offset0:204 offset1:220
	ds_write2_b32 v65, v16, v20 offset0:32 offset1:48
	ds_write2_b32 v65, v17, v21 offset0:100 offset1:116
	ds_write2_b32 v65, v18, v22 offset0:168 offset1:184
	ds_write2_b32 v65, v19, v23 offset0:236 offset1:252
	ds_write2_b32 v54, v8, v12 offset0:64 offset1:80
	ds_write2_b32 v54, v9, v13 offset0:132 offset1:148
	ds_write2_b32 v54, v10, v14 offset0:200 offset1:216
	ds_write2_b32 v55, v11, v15 offset0:12 offset1:28
	ds_write2_b32 v54, v0, v4 offset0:96 offset1:112
	ds_write2_b32 v54, v1, v5 offset0:164 offset1:180
	ds_write2_b32 v54, v2, v6 offset0:232 offset1:248
	ds_write2_b32 v55, v3, v7 offset0:44 offset1:60
	s_waitcnt lgkmcnt(0)
	s_barrier
	ds_read_b128 v[0:3], v57
	ds_read_b128 v[4:7], v57 offset:1088
	ds_read_b128 v[8:11], v57 offset:2176
	ds_read_b128 v[12:15], v57 offset:3264
	ds_read_b128 v[16:19], v57 offset:4352
	ds_read_b128 v[20:23], v57 offset:5440
	ds_read_b128 v[24:27], v57 offset:6528
	ds_read_b128 v[28:31], v57 offset:7616
	s_waitcnt vmcnt(8) lgkmcnt(0)
	v_pk_add_f32 v[0:1], v[210:211], v[0:1]
	v_pk_add_f32 v[2:3], v[212:213], v[2:3]
	global_store_dwordx4 v98, v[0:3], s[68:69]
	v_pk_add_f32 v[4:5], v[214:215], v[4:5]
	v_pk_add_f32 v[6:7], v[216:217], v[6:7]
	global_store_dwordx4 v99, v[4:7], s[68:69]
	v_pk_add_f32 v[8:9], v[218:219], v[8:9]
	v_pk_add_f32 v[10:11], v[220:221], v[10:11]
	global_store_dwordx4 v100, v[8:11], s[68:69]
	v_pk_add_f32 v[12:13], v[222:223], v[12:13]
	v_pk_add_f32 v[14:15], v[224:225], v[14:15]
	global_store_dwordx4 v101, v[12:15], s[68:69]
	v_pk_add_f32 v[16:17], v[226:227], v[16:17]
	v_pk_add_f32 v[18:19], v[228:229], v[18:19]
	global_store_dwordx4 v102, v[16:19], s[68:69]
	v_pk_add_f32 v[20:21], v[230:231], v[20:21]
	v_pk_add_f32 v[22:23], v[232:233], v[22:23]
	global_store_dwordx4 v103, v[20:23], s[68:69]
	v_pk_add_f32 v[24:25], v[234:235], v[24:25]
	v_pk_add_f32 v[26:27], v[236:237], v[26:27]
	global_store_dwordx4 v104, v[24:27], s[68:69]
	v_pk_add_f32 v[28:29], v[238:239], v[28:29]
	v_pk_add_f32 v[30:31], v[240:241], v[30:31]
	global_store_dwordx4 v105, v[28:31], s[68:69]
	s_cbranch_scc0 .LBB0_106
